# static s_setprio 1 for waves 4-7 across the FoX attention units (reset at P2 end), on top of the cb_scan move version
# speedup vs baseline: 1.0070x; 1.0070x over previous
; #define tid TIDX(wave)
; __global__ void __launch_bounds__(512, 2) fwd_kernel(Args args) {
;     ...
;         if (mixm & 2) { unsigned* qctr = (unsigned*)(ws + WS_CTL) + 64 * rep;
;             const attn_body::bf16 *qa_ = (const attn_body::bf16*)QA, *ka_ = (const attn_body::bf16*)KA, *va_ = (const attn_body::bf16*)VA; const float* lf_ = (const float*)(ws + WS_CBG);
;             for (;;) {
;                 if (tid == 0) MISC[0] = atomicAdd(qctr, 1u);
;                 __syncthreads();
;                 const int u = __builtin_amdgcn_readfirstlane((int)MISC[0]);
;                 __syncthreads();
;                 if (u >= 2048) break;
;                 attn_body::attn_unit<60>((u & 63) >> 3, u & 7, 31 - (u >> 6), qa_, ka_, va_, (attn_body::bf16*)OA, lf_, (const float*)(ws + WS_CTL) + 128, (char*)lds, wave);
;             } }
.LBB0_685:
	v_readlane_b32 s4, v246, 4
	s_nop 3
	s_cmp_lt_u32 s4, 4
	s_cbranch_scc1 .Lattn_prio_done
	s_setprio 1

; __device__ __forceinline__ unsigned xb_add(unsigned* p, unsigned v) { return __hip_atomic_fetch_add(p, v, __ATOMIC_RELAXED, __HIP_MEMORY_SCOPE_AGENT); }
; #define SEAM(k) do { if (IN(k) && IN((k) + 1)) { if ((k) == 0) cg::this_grid().sync(); else GSYNC(); } } while (0)
; __device__ __forceinline__ void xcd_barrier(const XcdBarrier& b, bool t0) {
;     asm volatile("s_waitcnt vmcnt(0)" ::: "memory");
;     __syncthreads();
;     if (t0) {
;         unsigned* bar = b.bar;
;         __builtin_amdgcn_s_waitcnt(0);
;         unsigned nloc = b.st[0], nx = b.st[1];
;         if (nloc == 0u) { xcd_barrier_complete(bar, b.x, nloc, nx); b.st[0] = nloc; b.st[1] = nx; }
;         const unsigned old = xb_add(&bar[XB_XSUB(b.x)], 1u);
;         const unsigned gen = old / nloc;
; __global__ void __launch_bounds__(512, 2) fwd_kernel(Args args) {
;     ...
;             } }
;     } }
;     SEAM(2);
.LBB0_786:
	s_setprio 0
	s_cmp_gt_i32 s86, 3
	s_cselect_b64 s[4:5], -1, 0
	s_and_b64 s[6:7], s[22:23], s[4:5]
	s_andn2_b64 vcc, exec, s[6:7]
	s_cbranch_vccnz .LBB0_840
	v_mbcnt_lo_u32_b32 v0, -1, 0
	v_mbcnt_hi_u32_b32 v0, -1, v0
	s_waitcnt vmcnt(0)
	s_waitcnt vmcnt(0) lgkmcnt(0)
	v_sub_u32_e32 v0, 0, v0
	v_cmp_eq_u32_e32 vcc, s74, v0
	s_barrier
	s_and_saveexec_b64 s[6:7], vcc
	s_cbranch_execz .LBB0_839
	s_mov_b32 s8, 0x20160
	s_addk_i32 s8, 0x100
	v_mov_b32_e32 v0, s8
	s_mov_b32 s8, 0x20164
	s_waitcnt vmcnt(0) expcnt(0) lgkmcnt(0)
	ds_read_b32 v2, v0
	s_addk_i32 s8, 0x100
	v_mov_b32_e32 v0, s8
	ds_read_b32 v0, v0
	s_waitcnt lgkmcnt(1)
	v_cmp_ne_u32_e32 vcc, 0, v2
	s_cbranch_vccnz .LBB0_803
	v_readlane_b32 s12, v246, 0
	v_readlane_b32 s13, v246, 1
	s_load_dwordx2 s[8:9], s[12:13], 0x4
	s_mov_b32 s13, 1
	v_mov_b32_e32 v16, 0
	s_waitcnt lgkmcnt(0)
	s_mul_i32 s12, s8, s88
	s_mul_i32 s12, s12, s9
	s_branch .LBB0_791
